# K-loop B-fragment LDS reads use one per-unit base register with immediate offsets (4 fewer VALU per iteration)
# baseline (speedup 1.0000x reference)
; #define PG8_STAGE(bufoff, gbase, ld) do { if ((bufoff) >= 4 * HTB) PG8_STAGE_(sRb, bufoff, gbase, ld); else PG8_STAGE_(sR, bufoff, gbase, ld); } while (0)
; #define PG8_LDA(dst, b, h) do { _Pragma("unroll") for (int m = 0; m < 4; ++m) _Pragma("unroll") for (int k = 0; k < 2; ++k) dst[m][k] = *(const LAS bf16x8*)(lds + PG8_SA(b, h) + aoff + m * 2048 + k * 1024); } while (0)
; #define PG8_LDB(dst, b, h) do { _Pragma("unroll") for (int n = 0; n < 2; ++n) _Pragma("unroll") for (int k = 0; k < 2; ++k) dst[n][k] = *(const LAS bf16x8*)(lds + PG8_SB(b, h) + boff + n * 2048 + k * 1024); } while (0)
; #define PG8_MMA(ai, bj, At, Bt) do { __builtin_amdgcn_s_setprio(1); _Pragma("unroll") for (int m = 0; m < 4; ++m) _Pragma("unroll") for (int n = 0; n < 2; ++n) _Pragma("unroll") for (int k = 0; k < 2; ++k) \
;         acc[ai][bj][m][n] = __builtin_amdgcn_mfma_f32_16x16x32_bf16(Bt[n][k], At[m][k], acc[ai][bj][m][n], 0, 0, 0); __builtin_amdgcn_s_setprio(0); } while (0)
; #define PG8_WAIT_V(n) asm volatile("s_waitcnt vmcnt(" #n ")" ::: "memory")
; #define PG8_WAIT_L(n) asm volatile("s_waitcnt lgkmcnt(" #n ")" ::: "memory")
; #define PG8_BAR __builtin_amdgcn_s_barrier()
; #define PG8_SCHED __builtin_amdgcn_sched_barrier(0)
; DI void gemm_phase(LAS unsigned char* lds, const Sched& S_, const Epi& E) {
;     ...
;     const int aoff = lds_byte(wr * 64 + fr, fq * 8), boff = lds_byte(wc * 32 + fr, fq * 8);
;     ...
;         for (int t = 0; t < nt; t += 2) {
;             const bool last = (t == nt - 2);
;             const char* a1 = cA + (size_t)(t + 1) * kstep;
;             const char* a2 = last ? nA : cA + (size_t)(t + 2) * kstep; const char* b2 = last ? nB : cB + (size_t)(t + 2) * kstep;
;             const char* a3 = a2 + kstep; const char* b3 = b2 + kstep;
;             const int l2a = last ? nlda : clda, l2b = last ? nldb : cldb; const size_t h2a = last ? nhA : hA, h2b = last ? nhB : hB;
;             PG8_LDB(B0, 0, 0); PG8_LDB(B1, 0, 1); PG8_SCHED; PG8_LDA(At, 0, 0); PG8_STAGE(PG8_SA(1, 1), a1 + hA, clda);
;             PG8_WAIT_V(8); PG8_WAIT_L(0); PG8_BAR; PG8_MMA(0, 0, At, B0); PG8_MMA(0, 1, At, B1); PG8_BAR; PG8_SCHED;
.LBB0_327:
	s_mov_b64 s[58:59], s[44:45]
	s_and_b64 s[44:45], s[28:29], exec
	s_mov_b64 s[74:75], s[50:51]
	s_mov_b32 s68, s70
	s_cselect_b32 s50, s47, s42
	s_mov_b32 s63, s57
	s_cselect_b32 s57, s59, s19
	s_cselect_b32 s70, s58, s18
	s_cselect_b32 s45, s75, s67
	s_cselect_b32 s44, s74, s66
	s_cselect_b32 s71, s68, s14
	s_ashr_i32 s43, s42, 31
	s_ashr_i32 s51, s50, 31
	s_mov_b32 s39, s47
	s_mov_b32 s23, s49
	s_mov_b32 s56, s48
	s_mov_b32 s22, s46
	s_lshl_b64 s[46:47], s[42:43], 7
	s_lshl_b64 s[48:49], s[50:51], 7
	s_add_i32 s82, s54, -2
	v_mul_lo_u32 v2, s42, v171
	v_add_u32_e32 v0, v2, v168
	v_mul_lo_u32 v4, s42, v221
	s_add_u32 s18, s18, 0x80
	v_add_u32_e32 v2, v226, v2
	v_mov_b32_e32 v3, v1
	s_waitcnt vmcnt(0)
	v_mad_u64_u32 v[132:133], s[42:43], s50, v171, v[168:169]
	v_mad_u64_u32 v[134:135], s[42:43], s50, v221, v[170:171]
	s_addc_u32 s19, s19, 0
	v_lshl_add_u64 v[136:137], s[46:47], 0, v[2:3]
	v_add_u32_e32 v2, v227, v4
	s_add_u32 s42, s66, 0x100
	v_lshl_add_u64 v[138:139], s[46:47], 0, v[2:3]
	v_mov_b32_e32 v2, 0
	s_mov_b32 s40, s81
	v_add_u32_e32 v130, v4, v170
	v_mov_b32_e32 v131, v1
	v_mov_b32_e32 v133, v1
	v_mov_b32_e32 v135, v1
	s_addc_u32 s43, s67, 0
	s_mov_b32 s83, 0
	v_mov_b64_e32 v[2:3], 0
	v_mov_b64_e32 v[4:5], 0
	v_mov_b64_e32 v[6:7], 0
	v_mov_b64_e32 v[8:9], 0
	v_mov_b64_e32 v[18:19], 0
	v_mov_b64_e32 v[20:21], 0
	v_mov_b64_e32 v[22:23], 0
	v_mov_b64_e32 v[24:25], 0
	v_mov_b64_e32 v[34:35], 0
	v_mov_b64_e32 v[36:37], 0
	v_mov_b64_e32 v[38:39], 0
	v_mov_b64_e32 v[40:41], 0
	v_mov_b64_e32 v[50:51], 0
	v_mov_b64_e32 v[52:53], 0
	v_mov_b64_e32 v[54:55], 0
	v_mov_b64_e32 v[56:57], 0
	v_mov_b64_e32 v[10:11], 0
	v_mov_b64_e32 v[12:13], 0
	v_mov_b64_e32 v[14:15], 0
	v_mov_b64_e32 v[16:17], 0
	v_mov_b64_e32 v[26:27], 0
	v_mov_b64_e32 v[28:29], 0
	v_mov_b64_e32 v[30:31], 0
	v_mov_b64_e32 v[32:33], 0
	v_mov_b64_e32 v[42:43], 0
	v_mov_b64_e32 v[44:45], 0
	v_mov_b64_e32 v[46:47], 0
	v_mov_b64_e32 v[48:49], 0
	v_mov_b64_e32 v[58:59], 0
	v_mov_b64_e32 v[60:61], 0
	v_mov_b64_e32 v[62:63], 0
	v_mov_b64_e32 v[64:65], 0
	v_mov_b64_e32 v[66:67], 0
	v_mov_b64_e32 v[68:69], 0
	v_mov_b64_e32 v[70:71], 0
	v_mov_b64_e32 v[72:73], 0
	v_mov_b64_e32 v[82:83], 0
	v_mov_b64_e32 v[84:85], 0
	v_mov_b64_e32 v[86:87], 0
	v_mov_b64_e32 v[88:89], 0
	v_mov_b64_e32 v[98:99], 0
	v_mov_b64_e32 v[100:101], 0
	v_mov_b64_e32 v[102:103], 0
	v_mov_b64_e32 v[104:105], 0
	v_mov_b64_e32 v[114:115], 0
	v_mov_b64_e32 v[116:117], 0
	v_mov_b64_e32 v[118:119], 0
	v_mov_b64_e32 v[120:121], 0
	v_mov_b64_e32 v[74:75], 0
	v_mov_b64_e32 v[76:77], 0
	v_mov_b64_e32 v[78:79], 0
	v_mov_b64_e32 v[80:81], 0
	v_mov_b64_e32 v[90:91], 0
	v_mov_b64_e32 v[92:93], 0
	v_mov_b64_e32 v[94:95], 0
	v_mov_b64_e32 v[96:97], 0
	v_mov_b64_e32 v[106:107], 0
	v_mov_b64_e32 v[108:109], 0
	v_mov_b64_e32 v[110:111], 0
	v_mov_b64_e32 v[112:113], 0
	v_mov_b64_e32 v[122:123], 0
	v_mov_b64_e32 v[124:125], 0
	v_mov_b64_e32 v[126:127], 0
	v_mov_b64_e32 v[128:129], 0
	v_add_u32_e32 v229, 0x10000, v225
	s_branch .LBB0_329
.LBB0_328:
	s_add_i32 s83, s83, 2
	s_add_u32 s77, s18, 0x80
	s_addc_u32 s84, s19, 0
	s_and_b64 s[80:81], exec, s[80:81]
	s_cselect_b32 s81, s57, s84
	s_cselect_b32 s80, s70, s77
	s_add_i32 s86, 0, 0x10000
	s_add_i32 s89, 0, 0x14000
	ds_read_b128 v[144:147], v229
	ds_read_b128 v[148:151], v229 offset:1024
	ds_read_b128 v[152:155], v229 offset:2048
	ds_read_b128 v[156:159], v229 offset:3072
	ds_read_b128 v[160:163], v229 offset:16384
	ds_read_b128 v[164:167], v229 offset:17408
	ds_read_b128 v[176:179], v229 offset:18432
	ds_read_b128 v[180:183], v229 offset:19456
	s_ashr_i32 s77, s76, 31
	v_lshl_add_u64 v[208:209], s[18:19], 0, v[136:137]
	s_add_i32 m0, s31, 0xc000
	ds_read_b128 v[184:187], v228
	ds_read_b128 v[188:191], v228 offset:1024
	ds_read_b128 v[192:195], v228 offset:2048
	ds_read_b128 v[196:199], v228 offset:3072
	ds_read_b128 v[200:203], v228 offset:4096
	ds_read_b128 v[204:207], v228 offset:5120
	ds_read_b128 v[236:239], v228 offset:6144
	ds_read_b128 v[240:243], v228 offset:7168
	global_load_lds_dwordx4 v[208:209], off
	v_lshl_add_u64 v[208:209], s[18:19], 0, v[138:139]
	s_add_i32 m0, s31, 0xe000
	s_nop 0
	global_load_lds_dwordx4 v[208:209], off
	s_waitcnt vmcnt(8)
	s_waitcnt lgkmcnt(0)
	s_barrier
	s_setprio 1
	s_waitcnt lgkmcnt(0)
	v_mfma_f32_16x16x32_bf16 v[126:129], v[144:147], v[184:187], v[126:129]
	v_mfma_f32_16x16x32_bf16 v[122:125], v[152:155], v[184:187], v[122:125]
	v_mfma_f32_16x16x32_bf16 v[110:113], v[144:147], v[192:195], v[110:113]
	v_mfma_f32_16x16x32_bf16 v[106:109], v[152:155], v[192:195], v[106:109]
	v_mfma_f32_16x16x32_bf16 v[94:97], v[144:147], v[200:203], v[94:97]
	v_mfma_f32_16x16x32_bf16 v[90:93], v[152:155], v[200:203], v[90:93]
	v_mfma_f32_16x16x32_bf16 v[78:81], v[144:147], v[236:239], v[78:81]
	v_mfma_f32_16x16x32_bf16 v[74:77], v[152:155], v[236:239], v[74:77]
	v_mfma_f32_16x16x32_bf16 v[126:129], v[148:151], v[188:191], v[126:129]
	v_mfma_f32_16x16x32_bf16 v[122:125], v[156:159], v[188:191], v[122:125]
	v_mfma_f32_16x16x32_bf16 v[110:113], v[148:151], v[196:199], v[110:113]
	v_mfma_f32_16x16x32_bf16 v[106:109], v[156:159], v[196:199], v[106:109]
	v_mfma_f32_16x16x32_bf16 v[94:97], v[148:151], v[204:207], v[94:97]
	v_mfma_f32_16x16x32_bf16 v[90:93], v[156:159], v[204:207], v[90:93]
	v_mfma_f32_16x16x32_bf16 v[78:81], v[148:151], v[240:243], v[78:81]
	v_mfma_f32_16x16x32_bf16 v[74:77], v[156:159], v[240:243], v[74:77]
	v_mfma_f32_16x16x32_bf16 v[118:121], v[160:163], v[184:187], v[118:121]
	v_mfma_f32_16x16x32_bf16 v[114:117], v[176:179], v[184:187], v[114:117]
	v_mfma_f32_16x16x32_bf16 v[102:105], v[160:163], v[192:195], v[102:105]
	v_mfma_f32_16x16x32_bf16 v[98:101], v[176:179], v[192:195], v[98:101]
	v_mfma_f32_16x16x32_bf16 v[86:89], v[160:163], v[200:203], v[86:89]
	v_mfma_f32_16x16x32_bf16 v[82:85], v[176:179], v[200:203], v[82:85]
	v_mfma_f32_16x16x32_bf16 v[70:73], v[160:163], v[236:239], v[70:73]
	v_mfma_f32_16x16x32_bf16 v[66:69], v[176:179], v[236:239], v[66:69]
	v_mfma_f32_16x16x32_bf16 v[118:121], v[164:167], v[188:191], v[118:121]
	v_mfma_f32_16x16x32_bf16 v[114:117], v[180:183], v[188:191], v[114:117]
	v_mfma_f32_16x16x32_bf16 v[102:105], v[164:167], v[196:199], v[102:105]
	v_mfma_f32_16x16x32_bf16 v[98:101], v[180:183], v[196:199], v[98:101]
	v_mfma_f32_16x16x32_bf16 v[86:89], v[164:167], v[204:207], v[86:89]
	v_mfma_f32_16x16x32_bf16 v[82:85], v[180:183], v[204:207], v[82:85]
	v_mfma_f32_16x16x32_bf16 v[70:73], v[164:167], v[240:243], v[70:73]
	v_mfma_f32_16x16x32_bf16 v[66:69], v[180:183], v[240:243], v[66:69]
	s_setprio 0
	s_barrier
; #define PG8_STAGE(bufoff, gbase, ld) do { if ((bufoff) >= 4 * HTB) PG8_STAGE_(sRb, bufoff, gbase, ld); else PG8_STAGE_(sR, bufoff, gbase, ld); } while (0)
; #define PG8_LDA(dst, b, h) do { _Pragma("unroll") for (int m = 0; m < 4; ++m) _Pragma("unroll") for (int k = 0; k < 2; ++k) dst[m][k] = *(const LAS bf16x8*)(lds + PG8_SA(b, h) + aoff + m * 2048 + k * 1024); } while (0)
; #define PG8_LDB(dst, b, h) do { _Pragma("unroll") for (int n = 0; n < 2; ++n) _Pragma("unroll") for (int k = 0; k < 2; ++k) dst[n][k] = *(const LAS bf16x8*)(lds + PG8_SB(b, h) + boff + n * 2048 + k * 1024); } while (0)
; #define PG8_MMA(ai, bj, At, Bt) do { __builtin_amdgcn_s_setprio(1); _Pragma("unroll") for (int m = 0; m < 4; ++m) _Pragma("unroll") for (int n = 0; n < 2; ++n) _Pragma("unroll") for (int k = 0; k < 2; ++k) \
;         acc[ai][bj][m][n] = __builtin_amdgcn_mfma_f32_16x16x32_bf16(Bt[n][k], At[m][k], acc[ai][bj][m][n], 0, 0, 0); __builtin_amdgcn_s_setprio(0); } while (0)
; #define PG8_WAIT_V(n) asm volatile("s_waitcnt vmcnt(" #n ")" ::: "memory")
; #define PG8_WAIT_L(n) asm volatile("s_waitcnt lgkmcnt(" #n ")" ::: "memory")
; #define PG8_BAR __builtin_amdgcn_s_barrier()
; #define PG8_SCHED __builtin_amdgcn_sched_barrier(0)
; DI void gemm_phase(LAS unsigned char* lds, const Sched& S_, const Epi& E) {
;     ...
;             PG8_LDA(At, 0, 1); PG8_STAGE(PG8_SB(0, 0), b2, l2b); PG8_STAGE(PG8_SB(0, 1), b2 + h2b, l2b); PG8_STAGE(PG8_SA(0, 0), a2, l2a);
;             PG8_WAIT_V(8); PG8_WAIT_L(0); PG8_BAR; PG8_MMA(1, 0, At, B0); PG8_MMA(1, 1, At, B1); PG8_BAR; PG8_SCHED;
;             PG8_LDB(B0, 1, 0); PG8_LDB(B1, 1, 1); PG8_SCHED; PG8_LDA(At, 1, 0); PG8_STAGE(PG8_SA(0, 1), a2 + h2a, l2a);
	s_add_i32 s86, s86, s30
	v_mad_u64_u32 v[208:209], s[84:85], s76, v220, v[168:169]
	s_mov_b32 m0, s86
	ds_read_b128 v[184:187], v228 offset:16384
	ds_read_b128 v[188:191], v228 offset:17408
	ds_read_b128 v[192:195], v228 offset:18432
	ds_read_b128 v[196:199], v228 offset:19456
	ds_read_b128 v[200:203], v228 offset:20480
	ds_read_b128 v[204:207], v228 offset:21504
	ds_read_b128 v[236:239], v228 offset:22528
	ds_read_b128 v[240:243], v228 offset:23552
	global_load_lds_dwordx4 v208, s[78:79]
	v_mad_u64_u32 v[244:245], s[84:85], s76, v222, v[170:171]
	s_add_i32 m0, s86, 0x2000
	s_lshl_b64 s[76:77], s[76:77], 7
	v_mov_b32_e32 v209, v1
	v_mov_b32_e32 v245, v1
	s_add_u32 s76, s78, s76
	v_lshl_add_u64 v[230:231], s[78:79], 0, v[208:209]
	v_lshl_add_u64 v[246:247], s[78:79], 0, v[244:245]
	global_load_lds_dwordx4 v244, s[78:79]
	s_addc_u32 s77, s79, s77
	s_add_i32 s78, s89, s30
	s_mov_b32 m0, s78
	v_lshl_add_u64 v[248:249], s[76:77], 0, v[208:209]
	global_load_lds_dwordx4 v208, s[76:77]
	s_add_i32 m0, s78, 0x2000
	v_lshl_add_u64 v[208:209], s[76:77], 0, v[244:245]
	global_load_lds_dwordx4 v244, s[76:77]
	v_lshl_add_u64 v[244:245], s[80:81], 0, v[142:143]
	s_mov_b32 m0, s31
	v_lshl_add_u64 v[250:251], s[80:81], 0, v[140:141]
	global_load_lds_dwordx4 v[244:245], off
	s_mov_b32 m0, s69
	s_nop 0
	global_load_lds_dwordx4 v[250:251], off
	s_waitcnt vmcnt(8)
	s_waitcnt lgkmcnt(0)
	s_barrier
	s_setprio 1
	s_waitcnt lgkmcnt(0)
	v_mfma_f32_16x16x32_bf16 v[62:65], v[144:147], v[184:187], v[62:65]
	v_mfma_f32_16x16x32_bf16 v[58:61], v[152:155], v[184:187], v[58:61]
	v_mfma_f32_16x16x32_bf16 v[46:49], v[144:147], v[192:195], v[46:49]
	v_mfma_f32_16x16x32_bf16 v[42:45], v[152:155], v[192:195], v[42:45]
	v_mfma_f32_16x16x32_bf16 v[30:33], v[144:147], v[200:203], v[30:33]
	v_mfma_f32_16x16x32_bf16 v[26:29], v[152:155], v[200:203], v[26:29]
	v_mfma_f32_16x16x32_bf16 v[14:17], v[144:147], v[236:239], v[14:17]
	v_mfma_f32_16x16x32_bf16 v[10:13], v[152:155], v[236:239], v[10:13]
	v_mfma_f32_16x16x32_bf16 v[62:65], v[148:151], v[188:191], v[62:65]
	v_mfma_f32_16x16x32_bf16 v[58:61], v[156:159], v[188:191], v[58:61]
	v_mfma_f32_16x16x32_bf16 v[46:49], v[148:151], v[196:199], v[46:49]
	v_mfma_f32_16x16x32_bf16 v[42:45], v[156:159], v[196:199], v[42:45]
	v_mfma_f32_16x16x32_bf16 v[30:33], v[148:151], v[204:207], v[30:33]
	v_mfma_f32_16x16x32_bf16 v[26:29], v[156:159], v[204:207], v[26:29]
	v_mfma_f32_16x16x32_bf16 v[14:17], v[148:151], v[240:243], v[14:17]
	v_mfma_f32_16x16x32_bf16 v[10:13], v[156:159], v[240:243], v[10:13]
	v_mfma_f32_16x16x32_bf16 v[54:57], v[160:163], v[184:187], v[54:57]
	v_mfma_f32_16x16x32_bf16 v[50:53], v[176:179], v[184:187], v[50:53]
	v_mfma_f32_16x16x32_bf16 v[38:41], v[160:163], v[192:195], v[38:41]
	v_mfma_f32_16x16x32_bf16 v[34:37], v[176:179], v[192:195], v[34:37]
	v_mfma_f32_16x16x32_bf16 v[22:25], v[160:163], v[200:203], v[22:25]
	v_mfma_f32_16x16x32_bf16 v[18:21], v[176:179], v[200:203], v[18:21]
	v_mfma_f32_16x16x32_bf16 v[6:9], v[160:163], v[236:239], v[6:9]
	v_mfma_f32_16x16x32_bf16 v[2:5], v[176:179], v[236:239], v[2:5]
	v_mfma_f32_16x16x32_bf16 v[54:57], v[164:167], v[188:191], v[54:57]
	v_mfma_f32_16x16x32_bf16 v[50:53], v[180:183], v[188:191], v[50:53]
	v_mfma_f32_16x16x32_bf16 v[38:41], v[164:167], v[196:199], v[38:41]
	v_mfma_f32_16x16x32_bf16 v[34:37], v[180:183], v[196:199], v[34:37]
	v_mfma_f32_16x16x32_bf16 v[22:25], v[164:167], v[204:207], v[22:25]
	v_mfma_f32_16x16x32_bf16 v[18:21], v[180:183], v[204:207], v[18:21]
	v_mfma_f32_16x16x32_bf16 v[6:9], v[164:167], v[240:243], v[6:9]
	v_mfma_f32_16x16x32_bf16 v[2:5], v[180:183], v[240:243], v[2:5]
	s_setprio 0
	s_barrier
	s_add_i32 s76, 0, 0x18000
	s_add_i32 s77, 0, 0x1c000
	ds_read_b128 v[144:147], v229 offset:32768
	ds_read_b128 v[148:151], v229 offset:33792
	ds_read_b128 v[152:155], v229 offset:34816
	ds_read_b128 v[156:159], v229 offset:35840
	ds_read_b128 v[160:163], v229 offset:49152
	ds_read_b128 v[164:167], v229 offset:50176
	ds_read_b128 v[176:179], v229 offset:51200
	ds_read_b128 v[180:183], v229 offset:52224
	s_add_u32 s50, s80, s50
	s_addc_u32 s51, s81, s51
	s_mov_b32 m0, s90
	v_lshl_add_u64 v[142:143], s[50:51], 0, v[142:143]
	ds_read_b128 v[184:187], v228 offset:32768
	ds_read_b128 v[188:191], v228 offset:33792
	ds_read_b128 v[192:195], v228 offset:34816
	ds_read_b128 v[196:199], v228 offset:35840
	ds_read_b128 v[200:203], v228 offset:36864
	ds_read_b128 v[204:207], v228 offset:37888
	ds_read_b128 v[236:239], v228 offset:38912
	ds_read_b128 v[240:243], v228 offset:39936
	global_load_lds_dwordx4 v[142:143], off
	v_lshl_add_u64 v[140:141], s[50:51], 0, v[140:141]
	s_mov_b32 m0, s91
	s_nop 0
	global_load_lds_dwordx4 v[140:141], off
	s_waitcnt vmcnt(8)
	s_waitcnt lgkmcnt(0)
	s_barrier
; #define PG8_STAGE(bufoff, gbase, ld) do { if ((bufoff) >= 4 * HTB) PG8_STAGE_(sRb, bufoff, gbase, ld); else PG8_STAGE_(sR, bufoff, gbase, ld); } while (0)
; #define PG8_LDA(dst, b, h) do { _Pragma("unroll") for (int m = 0; m < 4; ++m) _Pragma("unroll") for (int k = 0; k < 2; ++k) dst[m][k] = *(const LAS bf16x8*)(lds + PG8_SA(b, h) + aoff + m * 2048 + k * 1024); } while (0)
; #define PG8_MMA(ai, bj, At, Bt) do { __builtin_amdgcn_s_setprio(1); _Pragma("unroll") for (int m = 0; m < 4; ++m) _Pragma("unroll") for (int n = 0; n < 2; ++n) _Pragma("unroll") for (int k = 0; k < 2; ++k) \
;         acc[ai][bj][m][n] = __builtin_amdgcn_mfma_f32_16x16x32_bf16(Bt[n][k], At[m][k], acc[ai][bj][m][n], 0, 0, 0); __builtin_amdgcn_s_setprio(0); } while (0)
; #define PG8_WAIT_V(n) asm volatile("s_waitcnt vmcnt(" #n ")" ::: "memory")
; #define PG8_WAIT_L(n) asm volatile("s_waitcnt lgkmcnt(" #n ")" ::: "memory")
; #define PG8_BAR __builtin_amdgcn_s_barrier()
; #define PG8_SCHED __builtin_amdgcn_sched_barrier(0)
; DI void gemm_phase(LAS unsigned char* lds, const Sched& S_, const Epi& E) {
;     ...
;             PG8_WAIT_V(8); PG8_WAIT_L(0); PG8_BAR; PG8_MMA(0, 0, At, B0); PG8_MMA(0, 1, At, B1); PG8_BAR; PG8_SCHED;
;             PG8_LDA(At, 1, 1); PG8_STAGE(PG8_SB(1, 0), b3, l2b); PG8_STAGE(PG8_SB(1, 1), b3 + h2b, l2b); PG8_STAGE(PG8_SA(1, 0), a3, l2a);
;             PG8_WAIT_V(8); PG8_WAIT_L(0); PG8_BAR; PG8_MMA(1, 0, At, B0); PG8_MMA(1, 1, At, B1); PG8_BAR; PG8_SCHED;
	s_setprio 1
	s_waitcnt lgkmcnt(0)
	v_mfma_f32_16x16x32_bf16 v[126:129], v[144:147], v[184:187], v[126:129]
	v_mfma_f32_16x16x32_bf16 v[122:125], v[152:155], v[184:187], v[122:125]
	v_mfma_f32_16x16x32_bf16 v[110:113], v[144:147], v[192:195], v[110:113]
	v_mfma_f32_16x16x32_bf16 v[106:109], v[152:155], v[192:195], v[106:109]
	v_mfma_f32_16x16x32_bf16 v[94:97], v[144:147], v[200:203], v[94:97]
	v_mfma_f32_16x16x32_bf16 v[90:93], v[152:155], v[200:203], v[90:93]
	v_mfma_f32_16x16x32_bf16 v[78:81], v[144:147], v[236:239], v[78:81]
	v_mfma_f32_16x16x32_bf16 v[74:77], v[152:155], v[236:239], v[74:77]
	v_mfma_f32_16x16x32_bf16 v[126:129], v[148:151], v[188:191], v[126:129]
	v_mfma_f32_16x16x32_bf16 v[122:125], v[156:159], v[188:191], v[122:125]
	v_mfma_f32_16x16x32_bf16 v[110:113], v[148:151], v[196:199], v[110:113]
	v_mfma_f32_16x16x32_bf16 v[106:109], v[156:159], v[196:199], v[106:109]
	v_mfma_f32_16x16x32_bf16 v[94:97], v[148:151], v[204:207], v[94:97]
	v_mfma_f32_16x16x32_bf16 v[90:93], v[156:159], v[204:207], v[90:93]
	v_mfma_f32_16x16x32_bf16 v[78:81], v[148:151], v[240:243], v[78:81]
	v_mfma_f32_16x16x32_bf16 v[74:77], v[156:159], v[240:243], v[74:77]
	v_mfma_f32_16x16x32_bf16 v[118:121], v[160:163], v[184:187], v[118:121]
	v_mfma_f32_16x16x32_bf16 v[114:117], v[176:179], v[184:187], v[114:117]
	v_mfma_f32_16x16x32_bf16 v[102:105], v[160:163], v[192:195], v[102:105]
	v_mfma_f32_16x16x32_bf16 v[98:101], v[176:179], v[192:195], v[98:101]
	v_mfma_f32_16x16x32_bf16 v[86:89], v[160:163], v[200:203], v[86:89]
	v_mfma_f32_16x16x32_bf16 v[82:85], v[176:179], v[200:203], v[82:85]
	v_mfma_f32_16x16x32_bf16 v[70:73], v[160:163], v[236:239], v[70:73]
	v_mfma_f32_16x16x32_bf16 v[66:69], v[176:179], v[236:239], v[66:69]
	v_mfma_f32_16x16x32_bf16 v[118:121], v[164:167], v[188:191], v[118:121]
	v_mfma_f32_16x16x32_bf16 v[114:117], v[180:183], v[188:191], v[114:117]
	v_mfma_f32_16x16x32_bf16 v[102:105], v[164:167], v[196:199], v[102:105]
	v_mfma_f32_16x16x32_bf16 v[98:101], v[180:183], v[196:199], v[98:101]
	v_mfma_f32_16x16x32_bf16 v[86:89], v[164:167], v[204:207], v[86:89]
	v_mfma_f32_16x16x32_bf16 v[82:85], v[180:183], v[204:207], v[82:85]
	v_mfma_f32_16x16x32_bf16 v[70:73], v[164:167], v[240:243], v[70:73]
	v_mfma_f32_16x16x32_bf16 v[66:69], v[180:183], v[240:243], v[66:69]
	s_setprio 0
	s_barrier
	s_add_i32 s50, s76, s30
	v_lshl_add_u64 v[230:231], v[230:231], 0, s[34:35]
	s_mov_b32 m0, s50
	ds_read_b128 v[140:143], v228 offset:49152
	ds_read_b128 v[184:187], v228 offset:50176
	ds_read_b128 v[188:191], v228 offset:51200
	ds_read_b128 v[192:195], v228 offset:52224
	ds_read_b128 v[196:199], v228 offset:53248
	ds_read_b128 v[200:203], v228 offset:54272
	ds_read_b128 v[204:207], v228 offset:55296
	ds_read_b128 v[236:239], v228 offset:56320
	global_load_lds_dwordx4 v[230:231], off
	v_lshl_add_u64 v[230:231], v[246:247], 0, s[34:35]
	s_add_i32 m0, s50, 0x2000
	s_add_i32 s50, s77, s30
	global_load_lds_dwordx4 v[230:231], off
	v_lshl_add_u64 v[230:231], v[248:249], 0, s[34:35]
	s_mov_b32 m0, s50
	v_lshl_add_u64 v[208:209], v[208:209], 0, s[34:35]
	global_load_lds_dwordx4 v[230:231], off
	s_add_i32 m0, s50, 0x2000
	s_nop 0
	global_load_lds_dwordx4 v[208:209], off
	v_lshl_add_u64 v[208:209], v[244:245], 0, s[34:35]
	s_mov_b32 m0, s25
	s_nop 0
	global_load_lds_dwordx4 v[208:209], off
	v_lshl_add_u64 v[208:209], v[250:251], 0, s[34:35]
	s_mov_b32 m0, s26
	s_nop 0
	global_load_lds_dwordx4 v[208:209], off
	s_waitcnt vmcnt(8)
	s_waitcnt lgkmcnt(0)
	s_barrier
	s_setprio 1
	s_waitcnt lgkmcnt(0)
	v_mfma_f32_16x16x32_bf16 v[62:65], v[144:147], v[140:143], v[62:65]
	v_mfma_f32_16x16x32_bf16 v[58:61], v[152:155], v[140:143], v[58:61]
	v_mfma_f32_16x16x32_bf16 v[46:49], v[144:147], v[188:191], v[46:49]
	v_mfma_f32_16x16x32_bf16 v[42:45], v[152:155], v[188:191], v[42:45]
	v_mfma_f32_16x16x32_bf16 v[30:33], v[144:147], v[196:199], v[30:33]
	v_mfma_f32_16x16x32_bf16 v[26:29], v[152:155], v[196:199], v[26:29]
	v_mfma_f32_16x16x32_bf16 v[14:17], v[144:147], v[204:207], v[14:17]
	v_mfma_f32_16x16x32_bf16 v[10:13], v[152:155], v[204:207], v[10:13]
	v_mfma_f32_16x16x32_bf16 v[62:65], v[148:151], v[184:187], v[62:65]
	v_mfma_f32_16x16x32_bf16 v[58:61], v[156:159], v[184:187], v[58:61]
	v_mfma_f32_16x16x32_bf16 v[46:49], v[148:151], v[192:195], v[46:49]
	v_mfma_f32_16x16x32_bf16 v[42:45], v[156:159], v[192:195], v[42:45]
	v_mfma_f32_16x16x32_bf16 v[30:33], v[148:151], v[200:203], v[30:33]
	v_mfma_f32_16x16x32_bf16 v[26:29], v[156:159], v[200:203], v[26:29]
	v_mfma_f32_16x16x32_bf16 v[14:17], v[148:151], v[236:239], v[14:17]
	v_mfma_f32_16x16x32_bf16 v[10:13], v[156:159], v[236:239], v[10:13]
	v_mfma_f32_16x16x32_bf16 v[54:57], v[160:163], v[140:143], v[54:57]
	v_mfma_f32_16x16x32_bf16 v[50:53], v[176:179], v[140:143], v[50:53]
	v_mfma_f32_16x16x32_bf16 v[38:41], v[160:163], v[188:191], v[38:41]
	v_mfma_f32_16x16x32_bf16 v[34:37], v[176:179], v[188:191], v[34:37]
	v_mfma_f32_16x16x32_bf16 v[22:25], v[160:163], v[196:199], v[22:25]
	v_mfma_f32_16x16x32_bf16 v[18:21], v[176:179], v[196:199], v[18:21]
	v_mfma_f32_16x16x32_bf16 v[6:9], v[160:163], v[204:207], v[6:9]
	v_mfma_f32_16x16x32_bf16 v[2:5], v[176:179], v[204:207], v[2:5]
	v_mfma_f32_16x16x32_bf16 v[54:57], v[164:167], v[184:187], v[54:57]
	v_mfma_f32_16x16x32_bf16 v[50:53], v[180:183], v[184:187], v[50:53]
	v_mfma_f32_16x16x32_bf16 v[38:41], v[164:167], v[192:195], v[38:41]
	v_mfma_f32_16x16x32_bf16 v[34:37], v[180:183], v[192:195], v[34:37]
	v_mfma_f32_16x16x32_bf16 v[22:25], v[164:167], v[200:203], v[22:25]
	v_mfma_f32_16x16x32_bf16 v[18:21], v[180:183], v[200:203], v[18:21]
	v_mfma_f32_16x16x32_bf16 v[6:9], v[164:167], v[236:239], v[6:9]
	v_mfma_f32_16x16x32_bf16 v[2:5], v[180:183], v[236:239], v[2:5]
	s_setprio 0
	s_barrier
	s_add_u32 s18, s18, 0x100
	s_addc_u32 s19, s19, 0
	s_add_u32 s42, s42, 0x100
	s_addc_u32 s43, s43, 0
	s_cmp_ge_i32 s83, s54
	s_cbranch_scc1 .LBB0_331
